# P0 weight conversion: next item's loads stay in flight during the current item's LDS transpose and stores (wait + gain multiplies moved to the register hand-over)
# baseline (speedup 1.0000x reference)
; #define GAS __attribute__((address_space(1)))
; #define LAS __attribute__((address_space(3)))
; #define LDS_WAIT() asm volatile("s_waitcnt lgkmcnt(0)" ::: "memory")
; __device__ __forceinline__ unsigned pk2(float lo, float hi) { return f2bf(lo) | (f2bf(hi) << 16); }
; __device__ __forceinline__ void p0_load(const float* colp, int ldw, const float* gain, int k0, int lane, float (&w)[32]) {
; #pragma unroll
;     for (int i = 0; i < 32; ++i) { const int kk = 2 * i + (lane >> 5); float x = colp ? colp[(size_t)(k0 + kk) * ldw] : 0.f; if (gain) x *= gain[k0 + kk]; w[i] = x; }
; }
; __device__ __forceinline__ void p0_store(const float (&w)[32], int K, bf16* WT, int v0, int k0, LAS float* scr, int lane) {
; #pragma unroll
;     for (int i = 0; i < 32; ++i) { const int kk = 2 * i + (lane >> 5); scr[kk * 33 + (lane & 31)] = w[i]; }
;     LDS_WAIT(); asm volatile("" ::: "memory");
;     const int c = lane & 7;
; #pragma unroll
;     for (int j = 0; j < 4; ++j) { const int n = (lane >> 3) + 8 * j; const LAS float* s = scr + (8 * c) * 33 + n;
;         v4u o; o.x = pk2(s[0 * 33], s[1 * 33]); o.y = pk2(s[2 * 33], s[3 * 33]); o.z = pk2(s[4 * 33], s[5 * 33]); o.w = pk2(s[6 * 33], s[7 * 33]);
;         *(GAS v4u*)(WT + (size_t)(v0 + n) * K + k0 + 8 * c) = o; }
; __device__ __forceinline__ void p0_prologue(const Frame& F, const Args& A) {
;     ...
;         float wc[32]; int Kc = 0, v0c = 0, k0c = 0; bf16* WTc = nullptr;
;         if (gw < total) { const float* colp; const float* gain; int ldw; decode(gw, colp, ldw, gain, Kc, WTc, v0c, k0c); p0_load(colp, ldw, gain, k0c, lane, wc); }
;         for (int it = gw; it < total; it += NGW) {
;             float wn[32]; int Kn = 0, v0n = 0, k0n = 0; bf16* WTn = nullptr;
;             const bool more = it + NGW < total;
;             if (more) { const float* colp; const float* gain; int ldw; decode(it + NGW, colp, ldw, gain, Kn, WTn, v0n, k0n); p0_load(colp, ldw, gain, k0n, lane, wn); }
.LBB0_195:
	v_lshlrev_b32_e32 v34, 5, v100
	v_and_b32_e32 v74, 32, v34
	v_lshlrev_b32_e32 v34, 3, v100
	s_lshl_b32 s0, s89, 14
	v_ashrrev_i32_e32 v109, 3, v100
	v_and_b32_e32 v34, 56, v34
	s_add_i32 s0, s0, 0
	v_and_b32_e32 v1, 31, v100
	v_ashrrev_i32_e32 v68, 5, v100
	s_movk_i32 s1, 0x84
	v_mul_u32_u24_e32 v37, 0x84, v34
	v_lshlrev_b32_e32 v38, 2, v109
	v_lshl_add_u32 v35, v1, 2, s0
	v_mul_lo_u32 v36, v68, s1
	v_add3_u32 v110, s0, v37, v38
	v_readlane_b32 s0, v254, 2
	v_readlane_b32 s1, v254, 3
	s_load_dwordx8 s[8:15], s[0:1], 0xd8
	s_load_dwordx2 s[30:31], s[0:1], 0xc0
	s_load_dwordx8 s[16:23], s[0:1], 0xa0
	s_load_dwordx4 s[24:27], s[0:1], 0x60
	s_load_dwordx2 s[34:35], s[0:1], 0x70
	v_add_u32_e32 v75, 2, v68
	v_add_u32_e32 v76, 4, v68
	v_add_u32_e32 v77, 6, v68
	v_add_u32_e32 v78, 8, v68
	v_add_u32_e32 v79, 10, v68
	v_add_u32_e32 v80, 12, v68
	v_add_u32_e32 v81, 14, v68
	v_add_u32_e32 v82, 16, v68
	v_add_u32_e32 v83, 18, v68
	v_add_u32_e32 v84, 20, v68
	v_add_u32_e32 v85, 22, v68
	v_add_u32_e32 v86, 24, v68
	v_add_u32_e32 v87, 26, v68
	v_add_u32_e32 v88, 28, v68
	v_add_u32_e32 v89, 30, v68
	v_add_u32_e32 v90, 32, v68
	v_add_u32_e32 v91, 34, v68
	v_add_u32_e32 v92, 36, v68
	v_add_u32_e32 v93, 38, v68
	v_add_u32_e32 v94, 40, v68
	v_add_u32_e32 v95, 42, v68
	v_add_u32_e32 v96, 44, v68
	v_add_u32_e32 v97, 46, v68
	v_add_u32_e32 v101, 48, v68
	v_add_u32_e32 v102, 50, v68
	v_add_u32_e32 v103, 52, v68
	v_add_u32_e32 v104, 54, v68
	v_add_u32_e32 v105, 56, v68
	v_add_u32_e32 v106, 58, v68
	v_add_u32_e32 v107, 60, v68
	v_add_u32_e32 v108, 62, v68
	v_mov_b32_e32 v71, 0
	v_ashrrev_i32_e32 v69, 31, v68
	s_movk_i32 s0, 0x13ff
	s_movk_i32 s1, 0xec00
	s_movk_i32 s2, 0x1a20
	v_add_u32_e32 v111, v35, v36
	v_lshlrev_b32_e32 v70, 1, v34
	s_movk_i32 s52, 0x7fff
	s_mov_b32 s53, 0xffff0000
	s_mov_b32 s4, s94
	s_waitcnt vmcnt(0)
	s_branch .LBB0_197

; #define GAS __attribute__((address_space(1)))
; #define LAS __attribute__((address_space(3)))
; #define LDS_WAIT() asm volatile("s_waitcnt lgkmcnt(0)" ::: "memory")
; __device__ __forceinline__ unsigned pk2(float lo, float hi) { return f2bf(lo) | (f2bf(hi) << 16); }
; __device__ __forceinline__ void p0_load(const float* colp, int ldw, const float* gain, int k0, int lane, float (&w)[32]) {
;     ...
;     for (int i = 0; i < 32; ++i) { const int kk = 2 * i + (lane >> 5); float x = colp ? colp[(size_t)(k0 + kk) * ldw] : 0.f; if (gain) x *= gain[k0 + kk]; w[i] = x; }
; }
; __device__ __forceinline__ void p0_store(const float (&w)[32], int K, bf16* WT, int v0, int k0, LAS float* scr, int lane) {
; #pragma unroll
;     for (int i = 0; i < 32; ++i) { const int kk = 2 * i + (lane >> 5); scr[kk * 33 + (lane & 31)] = w[i]; }
;     LDS_WAIT(); asm volatile("" ::: "memory");
;     const int c = lane & 7;
; #pragma unroll
;     for (int j = 0; j < 4; ++j) { const int n = (lane >> 3) + 8 * j; const LAS float* s = scr + (8 * c) * 33 + n;
;         v4u o; o.x = pk2(s[0 * 33], s[1 * 33]); o.y = pk2(s[2 * 33], s[3 * 33]); o.z = pk2(s[4 * 33], s[5 * 33]); o.w = pk2(s[6 * 33], s[7 * 33]);
;         *(GAS v4u*)(WT + (size_t)(v0 + n) * K + k0 + 8 * c) = o; }
;     LDS_WAIT(); asm volatile("" ::: "memory");
.LBB0_381:
	s_or_b64 exec, exec, s[48:49]
	s_and_b64 vcc, exec, s[6:7]
	s_cbranch_vccnz .LBB0_383
	s_ashr_i32 s47, s46, 31
	v_lshl_add_u64 v[72:73], s[46:47], 0, v[68:69]
	v_lshl_add_u64 v[72:73], v[72:73], 2, s[40:41]
	global_load_dword v191, v[72:73], off offset:248
.LBB0_383:
	v_lshl_add_u64 v[72:73], v[98:99], 0, s[42:43]
.LBB0_384:
	v_add_u32_e32 v112, 0x400, v111
	ds_write2_b32 v111, v2, v3 offset1:66
	ds_write2_b32 v111, v4, v5 offset0:132 offset1:198
	ds_write2_b32 v112, v6, v7 offset0:8 offset1:74
	ds_write2_b32 v112, v8, v9 offset0:140 offset1:206
	v_add_u32_e32 v112, 0x800, v111
	ds_write2_b32 v112, v10, v11 offset0:16 offset1:82
	ds_write2_b32 v112, v12, v13 offset0:148 offset1:214
	v_add_u32_e32 v112, 0xc00, v111
	ds_write2_b32 v112, v14, v15 offset0:24 offset1:90
	ds_write2_b32 v112, v16, v17 offset0:156 offset1:222
	v_add_u32_e32 v112, 0x1000, v111
	ds_write2_b32 v112, v18, v19 offset0:32 offset1:98
	ds_write2_b32 v112, v20, v21 offset0:164 offset1:230
	v_add_u32_e32 v112, 0x1400, v111
	ds_write2_b32 v112, v22, v23 offset0:40 offset1:106
	ds_write2_b32 v112, v24, v25 offset0:172 offset1:238
	v_add_u32_e32 v112, 0x1800, v111
	ds_write2_b32 v112, v26, v27 offset0:48 offset1:114
	ds_write2_b32 v112, v28, v29 offset0:180 offset1:246
	v_add_u32_e32 v112, 0x1c00, v111
	ds_write2_b32 v112, v30, v31 offset0:56 offset1:122
	ds_write2_b32 v112, v32, v33 offset0:188 offset1:254
	s_waitcnt lgkmcnt(0)
	ds_read2_b32 v[116:117], v110 offset1:8
	ds_read2_b32 v[120:121], v110 offset0:33 offset1:41
	s_ashr_i32 s29, s28, 31
	ds_read2_b32 v[122:123], v110 offset0:66 offset1:74
	v_lshl_add_u64 v[112:113], s[28:29], 1, v[66:67]
	ds_read2_b32 v[124:125], v110 offset0:99 offset1:107
	v_lshl_add_u64 v[118:119], v[112:113], 0, v[70:71]
	s_waitcnt lgkmcnt(0)
	v_bfe_u32 v112, v116, 16, 1
	v_add3_u32 v112, v116, v112, s52
	v_bfe_u32 v113, v120, 16, 1
	ds_read2_b32 v[126:127], v110 offset0:132 offset1:140
	v_lshrrev_b32_e32 v112, 16, v112
	v_add3_u32 v113, v120, v113, s52
	ds_read2_b32 v[128:129], v110 offset0:165 offset1:173
	v_and_or_b32 v112, v113, s53, v112
	v_bfe_u32 v113, v122, 16, 1
	v_add3_u32 v113, v122, v113, s52
	v_bfe_u32 v114, v124, 16, 1
	ds_read2_b32 v[130:131], v110 offset0:198 offset1:206
	v_lshrrev_b32_e32 v113, 16, v113
	v_add3_u32 v114, v124, v114, s52
	ds_read2_b32 v[132:133], v110 offset0:231 offset1:239
	v_and_or_b32 v113, v114, s53, v113
	s_waitcnt lgkmcnt(3)
	v_bfe_u32 v114, v126, 16, 1
	v_add3_u32 v114, v126, v114, s52
	s_waitcnt lgkmcnt(2)
	v_bfe_u32 v115, v128, 16, 1
	v_lshrrev_b32_e32 v114, 16, v114
	v_add3_u32 v115, v128, v115, s52
	v_and_or_b32 v114, v115, s53, v114
	s_waitcnt lgkmcnt(1)
	v_bfe_u32 v115, v130, 16, 1
	v_add3_u32 v115, v130, v115, s52
	s_waitcnt lgkmcnt(0)
	v_bfe_u32 v116, v132, 16, 1
	v_add_u32_e32 v138, s51, v109
	v_lshrrev_b32_e32 v115, 16, v115
	v_add3_u32 v116, v132, v116, s52
	v_mad_u64_u32 v[134:135], s[4:5], v138, s50, 0
	v_and_or_b32 v115, v116, s53, v115
	v_ashrrev_i32_e32 v120, 31, v138
	v_mov_b32_e32 v116, v135
	v_mad_u64_u32 v[136:137], s[4:5], v120, s50, v[116:117]
	v_mov_b32_e32 v135, v136
	v_lshl_add_u64 v[134:135], v[134:135], 1, v[118:119]
	global_store_dwordx4 v[134:135], v[112:115], off
	v_bfe_u32 v116, v133, 16, 1
	v_add3_u32 v116, v133, v116, s52
	v_bfe_u32 v112, v117, 16, 1
	v_add3_u32 v112, v117, v112, s52
	v_bfe_u32 v113, v121, 16, 1
	v_lshrrev_b32_e32 v112, 16, v112
	v_add3_u32 v113, v121, v113, s52
	v_and_or_b32 v112, v113, s53, v112
	v_bfe_u32 v113, v123, 16, 1
	v_add3_u32 v113, v123, v113, s52
	v_bfe_u32 v114, v125, 16, 1
	v_lshrrev_b32_e32 v113, 16, v113
	v_add3_u32 v114, v125, v114, s52
	v_and_or_b32 v113, v114, s53, v113
	v_bfe_u32 v114, v127, 16, 1
	v_add3_u32 v114, v127, v114, s52
	v_bfe_u32 v115, v129, 16, 1
	v_lshrrev_b32_e32 v114, 16, v114
	v_add3_u32 v115, v129, v115, s52
	v_and_or_b32 v114, v115, s53, v114
	v_bfe_u32 v115, v131, 16, 1
	v_add3_u32 v115, v131, v115, s52
	v_lshrrev_b32_e32 v115, 16, v115
	v_and_or_b32 v115, v116, s53, v115
	v_add_u32_e32 v116, 8, v138
	v_ashrrev_i32_e32 v121, 31, v116
	v_mad_u64_u32 v[116:117], s[4:5], v116, s50, 0
	v_mov_b32_e32 v120, v117
	v_mad_u64_u32 v[120:121], s[4:5], v121, s50, v[120:121]
	v_mov_b32_e32 v117, v120
	ds_read2_b32 v[122:123], v110 offset0:16 offset1:24
	v_lshl_add_u64 v[116:117], v[116:117], 1, v[118:119]
	global_store_dwordx4 v[116:117], v[112:115], off
	ds_read2_b32 v[116:117], v110 offset0:49 offset1:57
	ds_read2_b32 v[120:121], v110 offset0:82 offset1:90
	ds_read2_b32 v[124:125], v110 offset0:115 offset1:123
	s_waitcnt lgkmcnt(3)
; #define GAS __attribute__((address_space(1)))
; #define LAS __attribute__((address_space(3)))
; #define LDS_WAIT() asm volatile("s_waitcnt lgkmcnt(0)" ::: "memory")
; __device__ __forceinline__ unsigned pk2(float lo, float hi) { return f2bf(lo) | (f2bf(hi) << 16); }
; __device__ __forceinline__ void p0_store(const float (&w)[32], int K, bf16* WT, int v0, int k0, LAS float* scr, int lane) {
; #pragma unroll
;     for (int i = 0; i < 32; ++i) { const int kk = 2 * i + (lane >> 5); scr[kk * 33 + (lane & 31)] = w[i]; }
;     LDS_WAIT(); asm volatile("" ::: "memory");
;     const int c = lane & 7;
; #pragma unroll
;     for (int j = 0; j < 4; ++j) { const int n = (lane >> 3) + 8 * j; const LAS float* s = scr + (8 * c) * 33 + n;
;         v4u o; o.x = pk2(s[0 * 33], s[1 * 33]); o.y = pk2(s[2 * 33], s[3 * 33]); o.z = pk2(s[4 * 33], s[5 * 33]); o.w = pk2(s[6 * 33], s[7 * 33]);
;         *(GAS v4u*)(WT + (size_t)(v0 + n) * K + k0 + 8 * c) = o; }
;     LDS_WAIT(); asm volatile("" ::: "memory");
; __device__ __forceinline__ void p0_prologue(const Frame& F, const Args& A) {
;     ...
;             if (more) { const float* colp; const float* gain; int ldw; decode(it + NGW, colp, ldw, gain, Kn, WTn, v0n, k0n); p0_load(colp, ldw, gain, k0n, lane, wn); }
;             p0_store(wc, Kc, WTc, v0c, k0c, scr, lane);
;             if (more) {
; #pragma unroll
;                 for (int i = 0; i < 32; ++i) wc[i] = wn[i];
;                 Kc = Kn; v0c = v0n; k0c = k0n; WTc = WTn; }
	v_bfe_u32 v112, v122, 16, 1
	v_add3_u32 v112, v122, v112, s52
	s_waitcnt lgkmcnt(2)
	v_bfe_u32 v113, v116, 16, 1
	ds_read2_b32 v[126:127], v110 offset0:148 offset1:156
	v_lshrrev_b32_e32 v112, 16, v112
	v_add3_u32 v113, v116, v113, s52
	ds_read2_b32 v[128:129], v110 offset0:181 offset1:189
	v_and_or_b32 v112, v113, s53, v112
	s_waitcnt lgkmcnt(3)
	v_bfe_u32 v113, v120, 16, 1
	v_add3_u32 v113, v120, v113, s52
	s_waitcnt lgkmcnt(2)
	v_bfe_u32 v114, v124, 16, 1
	ds_read2_b32 v[130:131], v110 offset0:214 offset1:222
	v_lshrrev_b32_e32 v113, 16, v113
	v_add3_u32 v114, v124, v114, s52
	ds_read2_b32 v[132:133], v110 offset0:247 offset1:255
	v_and_or_b32 v113, v114, s53, v113
	s_waitcnt lgkmcnt(3)
	v_bfe_u32 v114, v126, 16, 1
	v_add3_u32 v114, v126, v114, s52
	s_waitcnt lgkmcnt(2)
	v_bfe_u32 v115, v128, 16, 1
	v_lshrrev_b32_e32 v114, 16, v114
	v_add3_u32 v115, v128, v115, s52
	v_and_or_b32 v114, v115, s53, v114
	s_waitcnt lgkmcnt(1)
	v_bfe_u32 v115, v130, 16, 1
	v_add3_u32 v115, v130, v115, s52
	s_waitcnt lgkmcnt(0)
	v_bfe_u32 v116, v132, 16, 1
	v_lshrrev_b32_e32 v115, 16, v115
	v_add3_u32 v116, v132, v116, s52
	v_and_or_b32 v115, v116, s53, v115
	v_add_u32_e32 v116, 16, v138
	v_mad_u64_u32 v[134:135], s[4:5], v116, s50, 0
	v_ashrrev_i32_e32 v120, 31, v116
	v_mov_b32_e32 v116, v135
	v_mad_u64_u32 v[136:137], s[4:5], v120, s50, v[116:117]
	v_mov_b32_e32 v135, v136
	v_lshl_add_u64 v[134:135], v[134:135], 1, v[118:119]
	global_store_dwordx4 v[134:135], v[112:115], off
	v_bfe_u32 v116, v133, 16, 1
	v_add3_u32 v116, v133, v116, s52
	v_bfe_u32 v112, v123, 16, 1
	v_add3_u32 v112, v123, v112, s52
	v_bfe_u32 v113, v117, 16, 1
	v_lshrrev_b32_e32 v112, 16, v112
	v_add3_u32 v113, v117, v113, s52
	v_and_or_b32 v112, v113, s53, v112
	v_bfe_u32 v113, v121, 16, 1
	v_add3_u32 v113, v121, v113, s52
	v_bfe_u32 v114, v125, 16, 1
	v_lshrrev_b32_e32 v113, 16, v113
	v_add3_u32 v114, v125, v114, s52
	v_and_or_b32 v113, v114, s53, v113
	v_bfe_u32 v114, v127, 16, 1
	v_add3_u32 v114, v127, v114, s52
	v_bfe_u32 v115, v129, 16, 1
	v_lshrrev_b32_e32 v114, 16, v114
	v_add3_u32 v115, v129, v115, s52
	v_and_or_b32 v114, v115, s53, v114
	v_bfe_u32 v115, v131, 16, 1
	v_add3_u32 v115, v131, v115, s52
	v_lshrrev_b32_e32 v115, 16, v115
	v_and_or_b32 v115, v116, s53, v115
	v_add_u32_e32 v116, 24, v138
	v_ashrrev_i32_e32 v121, 31, v116
	v_mad_u64_u32 v[116:117], s[4:5], v116, s50, 0
	v_mov_b32_e32 v120, v117
	v_mad_u64_u32 v[120:121], s[4:5], v121, s50, v[120:121]
	v_mov_b32_e32 v117, v120
	v_lshl_add_u64 v[116:117], v[116:117], 1, v[118:119]
	global_store_dwordx4 v[116:117], v[112:115], off
	s_waitcnt lgkmcnt(0)
	s_andn2_b64 vcc, exec, s[38:39]
	s_cbranch_vccnz .LBB0_196
	s_waitcnt vmcnt(4)
	s_cmp_eq_u64 s[40:41], 0
	s_cbranch_scc1 .Lp0_nogain
	v_mul_f32_e32 v34, v34, v160
	v_mul_f32_e32 v35, v35, v161
	v_mul_f32_e32 v36, v36, v162
	v_mul_f32_e32 v37, v37, v163
	v_mul_f32_e32 v38, v38, v164
	v_mul_f32_e32 v39, v39, v165
	v_mul_f32_e32 v40, v40, v166
	v_mul_f32_e32 v41, v41, v167
	v_mul_f32_e32 v42, v42, v168
	v_mul_f32_e32 v43, v43, v169
	v_mul_f32_e32 v44, v44, v170
	v_mul_f32_e32 v45, v45, v171
	v_mul_f32_e32 v46, v46, v172
	v_mul_f32_e32 v47, v47, v173
	v_mul_f32_e32 v48, v48, v174
	v_mul_f32_e32 v49, v49, v175
	v_mul_f32_e32 v50, v50, v176
	v_mul_f32_e32 v51, v51, v177
	v_mul_f32_e32 v52, v52, v178
	v_mul_f32_e32 v53, v53, v179
	v_mul_f32_e32 v54, v54, v180
	v_mul_f32_e32 v55, v55, v181
	v_mul_f32_e32 v56, v56, v182
	v_mul_f32_e32 v57, v57, v183
	v_mul_f32_e32 v58, v58, v184
	v_mul_f32_e32 v59, v59, v185
	v_mul_f32_e32 v60, v60, v186
	v_mul_f32_e32 v61, v61, v187
	v_mul_f32_e32 v62, v62, v188
	v_mul_f32_e32 v63, v63, v189
	v_mul_f32_e32 v64, v64, v190
	v_mul_f32_e32 v65, v65, v191
.Lp0_nogain:
	v_mov_b64_e32 v[2:3], v[34:35]
	s_mov_b32 s28, s46
	v_mov_b64_e32 v[66:67], v[72:73]
	s_mov_b32 s51, s56
	s_mov_b32 s50, s55
	v_mov_b64_e32 v[4:5], v[36:37]
	v_mov_b64_e32 v[6:7], v[38:39]
	v_mov_b64_e32 v[8:9], v[40:41]
	v_mov_b64_e32 v[10:11], v[42:43]
	v_mov_b64_e32 v[12:13], v[44:45]
	v_mov_b64_e32 v[14:15], v[46:47]
	v_mov_b64_e32 v[16:17], v[48:49]
	v_mov_b64_e32 v[18:19], v[50:51]
	v_mov_b64_e32 v[20:21], v[52:53]
	v_mov_b64_e32 v[22:23], v[54:55]
	v_mov_b64_e32 v[24:25], v[56:57]
	v_mov_b64_e32 v[26:27], v[58:59]
	v_mov_b64_e32 v[28:29], v[60:61]
	v_mov_b64_e32 v[30:31], v[62:63]
	v_mov_b64_e32 v[32:33], v[64:65]
	s_branch .LBB0_196
